# v18 + NSA masked tiles: causal/window-tail mask as one v_cmp (per-lane constant) + v_cndmask per score instead of readlane+SALU mask algebra; filler s_nop removed from exp/PV
# speedup vs baseline: 1.0115x; 1.0044x over previous
; DI f32x16 mma32(bf16x8 a, bf16x8 b, f32x16 c) { return __builtin_amdgcn_mfma_f32_32x32x16_bf16(a, b, c, 0, 0, 0); }
; DI int crow(int i, int hf) { return (i & 3) + 8 * (i >> 2) + 4 * hf; }
; DI bf16x8 packp(const f32x16& x, const int h8) { v4u p; p.x = pk2(x[h8 + 0], x[h8 + 1]); p.y = pk2(x[h8 + 2], x[h8 + 3]); p.z = pk2(x[h8 + 4], x[h8 + 5]); p.w = pk2(x[h8 + 6], x[h8 + 7]); return __builtin_bit_cast(bf16x8, p); }
; DI void nsa_item(KA a, LAS unsigned char* lds, const int it) {
;     ...
;         f32x16 ot[2] = {ZERO16, ZERO16};
; #pragma unroll
;         for (int sp = 0; sp < 8; ++sp) { const bf16x8 pf = packp(st[sp >> 1], 8 * (sp & 1));
; #pragma unroll
;             for (int dh = 0; dh < 2; ++dh) ot[dh] = mma32(vfrag(VT, 32 * dh + r, sp, hf), pf, ot[dh]); }
;         of[0] = ot[0] * g0; of[1] = ot[1] * g0;
;     ...
;         if (mode != 0) {
; #pragma unroll
;             for (int kt = 0; kt < 2; ++kt)
; #pragma unroll
;                 for (int i2 = 0; i2 < 16; ++i2) { const int kl = 32 * kt + crow(i2, hf); const bool bad = rowoff || (mode == 1 && kl > tql) || (mode == 2 && kl <= tql); st[kt][i2] = bad ? -INFINITY : st[kt][i2]; }
.LBB0_794:
	v_add_f32_e32 v33, 1.0, v33
	v_rcp_f32_e32 v34, v33
	s_andn2_b64 vcc, exec, s[0:1]
	v_readlane_b32 s90, v254, 47
	v_pk_mul_f32 v[124:125], v[34:35], v[30:31] op_sel_hi:[0,1]
	v_pk_mul_f32 v[120:121], v[34:35], v[28:29] op_sel_hi:[0,1]
	v_pk_mul_f32 v[116:117], v[34:35], v[26:27] op_sel_hi:[0,1]
	v_pk_mul_f32 v[112:113], v[34:35], v[24:25] op_sel_hi:[0,1]
	v_pk_mul_f32 v[108:109], v[34:35], v[22:23] op_sel_hi:[0,1]
	v_pk_mul_f32 v[104:105], v[34:35], v[20:21] op_sel_hi:[0,1]
	v_pk_mul_f32 v[100:101], v[34:35], v[18:19] op_sel_hi:[0,1]
	v_pk_mul_f32 v[96:97], v[34:35], v[16:17] op_sel_hi:[0,1]
	v_pk_mul_f32 v[122:123], v[34:35], v[14:15] op_sel_hi:[0,1]
	v_pk_mul_f32 v[118:119], v[34:35], v[12:13] op_sel_hi:[0,1]
	v_pk_mul_f32 v[114:115], v[34:35], v[10:11] op_sel_hi:[0,1]
	v_pk_mul_f32 v[110:111], v[34:35], v[8:9] op_sel_hi:[0,1]
	v_pk_mul_f32 v[106:107], v[34:35], v[6:7] op_sel_hi:[0,1]
	v_pk_mul_f32 v[102:103], v[34:35], v[4:5] op_sel_hi:[0,1]
	v_pk_mul_f32 v[98:99], v[34:35], v[2:3] op_sel_hi:[0,1]
	v_pk_mul_f32 v[94:95], v[34:35], v[0:1] op_sel_hi:[0,1]
	v_mov_b32_e32 v31, 0
	s_cbranch_vccnz .LBB0_811
	v_cmp_gt_u32_e64 s[0:1], v92, v135
	v_or_b32_e32 v0, 2, v92
	s_sub_i32 s85, 23, s40
	v_writelane_b32 v254, s0, 49
	s_mov_b32 s87, 0
	s_mov_b32 s88, 0
	v_writelane_b32 v254, s1, 50
	v_cmp_le_u32_e64 s[0:1], v92, v135
	v_mov_b32_e32 v137, 0
	v_mov_b32_e32 v16, 0
	v_writelane_b32 v254, s0, 51
	s_nop 1
	v_writelane_b32 v254, s1, 52
	v_cmp_ge_u32_e64 s[0:1], v92, v135
	s_nop 1
	v_writelane_b32 v254, s0, 53
	s_nop 1
	v_writelane_b32 v254, s1, 54
	v_cmp_lt_u32_e64 s[0:1], v92, v135
	s_nop 1
	v_writelane_b32 v254, s0, 55
	s_nop 1
	v_writelane_b32 v254, s1, 56
	v_cmp_gt_u32_e64 s[0:1], v0, v135
	s_nop 1
	v_writelane_b32 v254, s0, 57
	s_nop 1
	v_writelane_b32 v254, s1, 58
	v_cmp_le_u32_e64 s[0:1], v0, v135
	v_or_b32_e32 v0, 3, v92
	s_nop 0
	v_writelane_b32 v254, s0, 59
	s_nop 1
	v_writelane_b32 v254, s1, 60
	v_cmp_gt_u32_e64 s[0:1], v0, v135
	s_nop 1
	v_writelane_b32 v254, s0, 61
	s_nop 1
	v_writelane_b32 v254, s1, 62
	v_cmp_le_u32_e64 s[0:1], v0, v135
	v_or_b32_e32 v0, 8, v92
	s_nop 0
	v_writelane_b32 v254, s0, 63
	s_nop 0
	v_readlane_b32 s86, v254, 13
	v_writelane_b32 v245, s1, 0
	v_cmp_gt_u32_e64 s[0:1], v0, v135
	s_nop 1
	v_writelane_b32 v245, s0, 1
	s_nop 1
	v_writelane_b32 v245, s1, 2
	v_cmp_le_u32_e64 s[0:1], v0, v135
	v_or_b32_e32 v0, 9, v92
	s_nop 0
	v_writelane_b32 v245, s0, 3
	s_nop 1
	v_writelane_b32 v245, s1, 4
	v_cmp_gt_u32_e64 s[0:1], v0, v135
	s_nop 1
	v_writelane_b32 v245, s0, 5
	s_nop 1
	v_writelane_b32 v245, s1, 6
	v_cmp_le_u32_e64 s[0:1], v0, v135
	v_or_b32_e32 v0, 10, v92
	s_nop 0
	v_writelane_b32 v245, s0, 7
	s_nop 1
	v_writelane_b32 v245, s1, 8
	v_cmp_gt_u32_e64 s[0:1], v0, v135
	s_nop 1
	v_writelane_b32 v245, s0, 9
	s_nop 1
	v_writelane_b32 v245, s1, 10
	v_cmp_le_u32_e64 s[0:1], v0, v135
	v_or_b32_e32 v0, 11, v92
	s_nop 0
	v_writelane_b32 v245, s0, 11
	s_nop 1
	v_writelane_b32 v245, s1, 12
	v_cmp_gt_u32_e64 s[0:1], v0, v135
	s_nop 1
	v_writelane_b32 v245, s0, 13
	s_nop 1
	v_writelane_b32 v245, s1, 14
	v_cmp_le_u32_e64 s[0:1], v0, v135
	v_or_b32_e32 v0, 16, v92
	s_nop 0
	v_writelane_b32 v245, s0, 15
	s_nop 1
	v_writelane_b32 v245, s1, 16
	v_cmp_gt_u32_e64 s[0:1], v0, v135
	s_nop 1
	v_writelane_b32 v245, s0, 17
	s_nop 1
	v_writelane_b32 v245, s1, 18
	v_cmp_le_u32_e64 s[0:1], v0, v135
	v_or_b32_e32 v0, 17, v92
	s_nop 0
	v_writelane_b32 v245, s0, 19
	s_nop 1
	v_writelane_b32 v245, s1, 20
	v_cmp_gt_u32_e64 s[0:1], v0, v135
	s_nop 1
	v_writelane_b32 v245, s0, 21
	s_nop 1
	v_writelane_b32 v245, s1, 22
	v_cmp_le_u32_e64 s[0:1], v0, v135
	v_or_b32_e32 v0, 18, v92
	s_nop 0
	v_writelane_b32 v245, s0, 23
	s_nop 1
	v_writelane_b32 v245, s1, 24
	v_cmp_gt_u32_e64 s[0:1], v0, v135
	s_nop 1
	v_writelane_b32 v245, s0, 25
	s_nop 1
	v_writelane_b32 v245, s1, 26
	v_cmp_le_u32_e64 s[0:1], v0, v135
	v_or_b32_e32 v0, 19, v92
	s_nop 0
	v_writelane_b32 v245, s0, 27
	s_nop 1
	v_writelane_b32 v245, s1, 28
	v_cmp_gt_u32_e64 s[0:1], v0, v135
	s_nop 1
	v_writelane_b32 v245, s0, 29
	s_nop 1
	v_writelane_b32 v245, s1, 30
	v_cmp_le_u32_e64 s[0:1], v0, v135
; __device__ __forceinline__ int tid_() { int t = threadIdx.x; asm volatile("" : "+v"(t)); return t; }
; DI int crow(int i, int hf) { return (i & 3) + 8 * (i >> 2) + 4 * hf; }
; DI void nsa_item(KA a, LAS unsigned char* lds, const int it) {
;     const int tid = tid_(), lane = tid & 63, w = tid >> 6, r = lane & 31, hf = lane >> 5;
;     const int qb = 31 - (it >> 5), bg = it & 31, b = bg >> 1, g = bg & 1, hh = w >> 1, head = g * 4 + hh, tql = 32 * (w & 1) + r;
;     ...
;         if (mode != 0) {
; #pragma unroll
;             for (int kt = 0; kt < 2; ++kt)
; #pragma unroll
;                 for (int i2 = 0; i2 < 16; ++i2) { const int kl = 32 * kt + crow(i2, hf); const bool bad = rowoff || (mode == 1 && kl > tql) || (mode == 2 && kl <= tql); st[kt][i2] = bad ? -INFINITY : st[kt][i2]; }
	v_or_b32_e32 v0, 24, v92
	s_nop 0
	v_writelane_b32 v245, s0, 31
	s_nop 1
	v_writelane_b32 v245, s1, 32
	v_cmp_gt_u32_e64 s[0:1], v0, v135
	s_nop 1
	v_writelane_b32 v245, s0, 33
	s_nop 1
	v_writelane_b32 v245, s1, 34
	v_cmp_le_u32_e64 s[0:1], v0, v135
	v_or_b32_e32 v0, 25, v92
	v_cmp_gt_u32_e64 s[92:93], v0, v135
	v_cmp_le_u32_e64 s[94:95], v0, v135
	v_or_b32_e32 v0, 26, v92
	v_cmp_gt_u32_e64 s[96:97], v0, v135
	v_cmp_le_u32_e64 s[6:7], v0, v135
	v_or_b32_e32 v0, 27, v92
	v_cmp_gt_u32_e64 s[8:9], v0, v135
	v_cmp_le_u32_e64 s[10:11], v0, v135
	v_or_b32_e32 v0, 32, v92
	v_cmp_gt_u32_e64 s[12:13], v0, v135
	v_cmp_le_u32_e64 s[14:15], v0, v135
	v_or_b32_e32 v0, 33, v92
	v_cmp_gt_u32_e64 s[16:17], v0, v135
	v_cmp_le_u32_e64 s[18:19], v0, v135
	v_or_b32_e32 v0, 34, v92
	v_cmp_gt_u32_e64 s[20:21], v0, v135
	v_cmp_le_u32_e64 s[22:23], v0, v135
	v_or_b32_e32 v0, 35, v92
	v_cmp_gt_u32_e64 s[24:25], v0, v135
	v_cmp_le_u32_e64 s[26:27], v0, v135
	v_or_b32_e32 v0, 40, v92
	v_cmp_gt_u32_e64 s[28:29], v0, v135
	v_cmp_le_u32_e64 s[30:31], v0, v135
	v_or_b32_e32 v0, 41, v92
	v_cmp_gt_u32_e64 s[34:35], v0, v135
	v_cmp_le_u32_e64 s[36:37], v0, v135
	v_or_b32_e32 v0, 42, v92
	v_cmp_gt_u32_e64 s[38:39], v0, v135
	v_cmp_le_u32_e64 s[4:5], v0, v135
	v_or_b32_e32 v0, 43, v92
	v_writelane_b32 v245, s0, 35
	v_cmp_gt_u32_e64 s[40:41], v0, v135
	v_cmp_le_u32_e64 s[2:3], v0, v135
	v_or_b32_e32 v0, 48, v92
	v_writelane_b32 v245, s1, 36
	v_cmp_gt_u32_e64 s[0:1], v0, v135
	v_cmp_le_u32_e64 s[42:43], v0, v135
	v_or_b32_e32 v0, 49, v92
	v_cmp_gt_u32_e64 s[44:45], v0, v135
	v_cmp_le_u32_e64 s[46:47], v0, v135
	v_or_b32_e32 v0, 50, v92
	v_cmp_gt_u32_e64 s[48:49], v0, v135
	v_cmp_le_u32_e64 s[50:51], v0, v135
	v_or_b32_e32 v0, 51, v92
	v_cmp_gt_u32_e64 s[52:53], v0, v135
	v_cmp_le_u32_e64 s[54:55], v0, v135
	v_or_b32_e32 v0, 56, v92
	v_cmp_gt_u32_e64 s[56:57], v0, v135
	v_cmp_le_u32_e64 s[58:59], v0, v135
	v_or_b32_e32 v0, 57, v92
	v_cmp_gt_u32_e64 s[60:61], v0, v135
	v_cmp_le_u32_e64 s[62:63], v0, v135
	v_or_b32_e32 v0, 58, v92
	v_cmp_gt_u32_e64 s[64:65], v0, v135
	v_cmp_le_u32_e64 s[66:67], v0, v135
	v_or_b32_e32 v0, 59, v92
	v_cmp_gt_u32_e64 s[68:69], v0, v135
	v_cmp_le_u32_e64 s[70:71], v0, v135
	v_mov_b32_e32 v135, 0
	v_mov_b32_e32 v0, 0
	v_mov_b32_e32 v1, v135
	v_mov_b32_e32 v2, v135
	v_mov_b32_e32 v3, v135
	v_mov_b32_e32 v4, v135
	v_mov_b32_e32 v5, v135
	v_mov_b32_e32 v6, v135
	v_mov_b32_e32 v7, v135
	v_mov_b32_e32 v8, v135
	v_mov_b32_e32 v9, v135
	v_mov_b32_e32 v10, v135
	v_mov_b32_e32 v11, v135
	v_mov_b32_e32 v12, v135
	v_mov_b32_e32 v13, v135
	v_mov_b32_e32 v14, v135
	v_mov_b32_e32 v15, v135
	v_mov_b32_e32 v17, v135
	v_mov_b32_e32 v18, v135
	v_mov_b32_e32 v19, v135
	v_mov_b32_e32 v20, v135
	v_mov_b32_e32 v21, v135
	v_mov_b32_e32 v22, v135
	v_mov_b32_e32 v23, v135
	v_mov_b32_e32 v24, v135
	v_mov_b32_e32 v25, v135
	v_mov_b32_e32 v26, v135
	v_mov_b32_e32 v27, v135
	v_mov_b32_e32 v28, v135
	v_mov_b32_e32 v29, v135
	v_mov_b32_e32 v30, v135
	v_mov_b32_e32 v31, v135
	s_movk_i32 s74, 0x1c00
	v_mad_u32_u24 v190, v132, s74, v192
	v_mad_u32_u24 v251, v133, s74, v88
	v_add_u32_e32 v241, 0x1c00, v251
	v_and_b32_e32 v242, 31, v238
	v_lshrrev_b32_e32 v243, 5, v238
	v_lshlrev_b32_e32 v243, 2, v243
	v_sub_u32_e32 v242, v242, v243
	v_bfe_u32 v243, v232, 6, 1
	v_lshl_add_u32 v242, v243, 5, v242
	v_add3_u32 v231, 0, v90, v130
	s_movk_i32 s74, 0x4800
	v_add3_u32 v230, s74, v90, v131
	ds_read_b128 v[170:173], v231 offset:64
	ds_read_b128 v[178:181], v231 offset:4608
	ds_read_b128 v[182:185], v231 offset:4640
	ds_read_b128 v[186:189], v231 offset:4672
	ds_read_b128 v[206:209], v231 offset:4704
	ds_read_b128 v[174:177], v231 offset:96
	s_add_i32 s74, s86, -8
	v_mov_b32_e32 v191, s74
	ds_read_b32 v191, v191
	v_mov_b32_e32 v250, s86
	ds_read_b32 v250, v250
	ds_read_b128 v[210:213], v230
	ds_read_b128 v[218:221], v230 offset:8704
	ds_read_b128 v[222:225], v230 offset:8736
	ds_read_b128 v[214:217], v230 offset:32
	ds_read_b128 v[226:229], v230 offset:64
	ds_read_b128 v[152:155], v230 offset:8768
	ds_read_b128 v[246:249], v230 offset:96
	ds_read_b128 v[144:147], v231
	ds_read_b128 v[148:151], v231 offset:32

; DI int crow(int i, int hf) { return (i & 3) + 8 * (i >> 2) + 4 * hf; }
; DI void nsa_item(KA a, LAS unsigned char* lds, const int it) {
;     ...
;         if (mode != 0) {
; #pragma unroll
;             for (int kt = 0; kt < 2; ++kt)
; #pragma unroll
;                 for (int i2 = 0; i2 < 16; ++i2) { const int kl = 32 * kt + crow(i2, hf); const bool bad = rowoff || (mode == 1 && kl > tql) || (mode == 2 && kl <= tql); st[kt][i2] = bad ? -INFINITY : st[kt][i2]; }
;         }
.LBB0_798:
	s_and_b32 s83, s78, 0xff
	s_cmpk_lt_u32 s78, 0x100
	s_cselect_b64 s[80:81], -1, 0
	s_lshl_b32 s78, 1, s78
	v_and_b32_e32 v32, s78, v141
	v_cmp_eq_u32_e32 vcc, 0, v32
	s_and_b64 s[78:79], s[80:81], vcc
	v_cndmask_b32_e64 v32, -v137, v240, s[78:79]
	v_mov_b32_e32 v33, v32
	v_mov_b32_e32 v34, v32
	v_mov_b32_e32 v35, v32
	v_mov_b32_e32 v36, v32
	v_mov_b32_e32 v37, v32
	v_mov_b32_e32 v38, v32
	v_mov_b32_e32 v39, v32
	v_mov_b32_e32 v40, v32
	v_mov_b32_e32 v41, v32
	v_mov_b32_e32 v42, v32
	v_mov_b32_e32 v43, v32
	v_mov_b32_e32 v44, v32
	v_mov_b32_e32 v45, v32
	v_mov_b32_e32 v46, v32
	v_mov_b32_e32 v47, v32
	s_cmp_eq_u32 s83, s90
	s_cselect_b64 s[80:81], -1, 0
	s_nop 0
	v_mfma_f32_32x32x16_bf16 v[48:63], v[170:173], v[68:71], v[32:47]
	s_cmp_eq_u32 s83, s85
	s_cselect_b64 vcc, -1, 0
	s_cmp_eq_u32 s82, 1
	s_cselect_b64 s[82:83], -1, 0
	s_and_b64 s[82:83], s[82:83], vcc
	s_or_b64 vcc, s[80:81], s[82:83]
	s_andn2_b64 vcc, exec, vcc
	v_mfma_f32_32x32x16_bf16 v[32:47], v[178:181], v[72:75], v[32:47]
	v_mfma_f32_32x32x16_bf16 v[32:47], v[182:185], v[64:67], v[32:47]
	v_mfma_f32_32x32x16_bf16 v[32:47], v[186:189], v[68:71], v[32:47]
	v_mfma_f32_32x32x16_bf16 v[32:47], v[206:209], v[76:79], v[32:47]
	v_mfma_f32_32x32x16_bf16 v[48:63], v[174:177], v[76:79], v[48:63]
	s_waitcnt lgkmcnt(1)
	v_mfma_f32_32x32x16_bf16 v[48:63], v[144:147], v[72:75], v[48:63]
	s_waitcnt lgkmcnt(0)
	v_mfma_f32_32x32x16_bf16 v[48:63], v[148:151], v[64:67], v[48:63]
	ds_read_b128 v[148:151], v230 offset:8800
	s_cbranch_vccnz .LBB0_800
	s_and_b64 vcc, exec, s[80:81]
	s_nop 0
	s_cbranch_vccz .Lnsa_m2
	v_cmp_gt_i32_e64 s[74:75], 32, v242
	v_cmp_gt_i32_e64 s[76:77], 33, v242
	v_cmp_gt_i32_e64 s[78:79], 34, v242
	v_cndmask_b32_e64 v32, v32, v240, s[74:75]
	v_cmp_gt_i32_e64 s[74:75], 35, v242
	v_cndmask_b32_e64 v33, v33, v240, s[76:77]
	v_cmp_gt_i32_e64 s[76:77], 40, v242
	v_cndmask_b32_e64 v34, v34, v240, s[78:79]
	v_cmp_gt_i32_e64 s[78:79], 41, v242
	v_cndmask_b32_e64 v35, v35, v240, s[74:75]
	v_cmp_gt_i32_e64 s[74:75], 42, v242
	v_cndmask_b32_e64 v36, v36, v240, s[76:77]
	v_cmp_gt_i32_e64 s[76:77], 43, v242
	v_cndmask_b32_e64 v37, v37, v240, s[78:79]
	v_cmp_gt_i32_e64 s[78:79], 48, v242
	v_cndmask_b32_e64 v38, v38, v240, s[74:75]
	v_cmp_gt_i32_e64 s[74:75], 49, v242
	v_cndmask_b32_e64 v39, v39, v240, s[76:77]
	v_cmp_gt_i32_e64 s[76:77], 50, v242
	v_cndmask_b32_e64 v40, v40, v240, s[78:79]
	v_cmp_gt_i32_e64 s[78:79], 51, v242
	v_cndmask_b32_e64 v41, v41, v240, s[74:75]
	v_cmp_gt_i32_e64 s[74:75], 56, v242
	v_cndmask_b32_e64 v42, v42, v240, s[76:77]
	v_cmp_gt_i32_e64 s[76:77], 57, v242
	v_cndmask_b32_e64 v43, v43, v240, s[78:79]
	v_cmp_gt_i32_e64 s[78:79], 58, v242
	v_cndmask_b32_e64 v44, v44, v240, s[74:75]
	v_cmp_gt_i32_e64 s[74:75], 59, v242
	v_cndmask_b32_e64 v45, v45, v240, s[76:77]
	v_cmp_gt_i32_e64 s[76:77], 0, v242
	v_cndmask_b32_e64 v46, v46, v240, s[78:79]
	v_cmp_gt_i32_e64 s[78:79], 1, v242
	v_cndmask_b32_e64 v47, v47, v240, s[74:75]
	v_cmp_gt_i32_e64 s[74:75], 2, v242
	v_cndmask_b32_e64 v48, v48, v240, s[76:77]
	v_cmp_gt_i32_e64 s[76:77], 3, v242
	v_cndmask_b32_e64 v49, v49, v240, s[78:79]
	v_cmp_gt_i32_e64 s[78:79], 8, v242
	v_cndmask_b32_e64 v50, v50, v240, s[74:75]
	v_cmp_gt_i32_e64 s[74:75], 9, v242
	v_cndmask_b32_e64 v51, v51, v240, s[76:77]
	v_cmp_gt_i32_e64 s[76:77], 10, v242
	v_cndmask_b32_e64 v52, v52, v240, s[78:79]
	v_cmp_gt_i32_e64 s[78:79], 11, v242
	v_cndmask_b32_e64 v53, v53, v240, s[74:75]
	v_cmp_gt_i32_e64 s[74:75], 16, v242
	v_cndmask_b32_e64 v54, v54, v240, s[76:77]
	v_cmp_gt_i32_e64 s[76:77], 17, v242
	v_cndmask_b32_e64 v55, v55, v240, s[78:79]
	v_cmp_gt_i32_e64 s[78:79], 18, v242
	v_cndmask_b32_e64 v56, v56, v240, s[74:75]
	v_cmp_gt_i32_e64 s[74:75], 19, v242
	v_cndmask_b32_e64 v57, v57, v240, s[76:77]
	v_cmp_gt_i32_e64 s[76:77], 24, v242
	v_cndmask_b32_e64 v58, v58, v240, s[78:79]
	v_cmp_gt_i32_e64 s[78:79], 25, v242
	v_cndmask_b32_e64 v59, v59, v240, s[74:75]
	v_cmp_gt_i32_e64 s[74:75], 26, v242
	v_cndmask_b32_e64 v60, v60, v240, s[76:77]
	v_cmp_gt_i32_e64 s[76:77], 27, v242
	s_nop 0
	v_cndmask_b32_e64 v61, v61, v240, s[78:79]
	v_cndmask_b32_e64 v62, v62, v240, s[74:75]
	v_cndmask_b32_e64 v63, v63, v240, s[76:77]
	s_branch .LBB0_800
.Lnsa_m2:
	v_cmp_le_i32_e64 s[74:75], 32, v242
	v_cmp_le_i32_e64 s[76:77], 33, v242
	v_cmp_le_i32_e64 s[78:79], 34, v242
	v_cndmask_b32_e64 v32, v32, v240, s[74:75]
	v_cmp_le_i32_e64 s[74:75], 35, v242
	v_cndmask_b32_e64 v33, v33, v240, s[76:77]
	v_cmp_le_i32_e64 s[76:77], 40, v242
	v_cndmask_b32_e64 v34, v34, v240, s[78:79]
	v_cmp_le_i32_e64 s[78:79], 41, v242
	v_cndmask_b32_e64 v35, v35, v240, s[74:75]
	v_cmp_le_i32_e64 s[74:75], 42, v242
	v_cndmask_b32_e64 v36, v36, v240, s[76:77]
	v_cmp_le_i32_e64 s[76:77], 43, v242
	v_cndmask_b32_e64 v37, v37, v240, s[78:79]
	v_cmp_le_i32_e64 s[78:79], 48, v242
	v_cndmask_b32_e64 v38, v38, v240, s[74:75]
	v_cmp_le_i32_e64 s[74:75], 49, v242
	v_cndmask_b32_e64 v39, v39, v240, s[76:77]
	v_cmp_le_i32_e64 s[76:77], 50, v242
	v_cndmask_b32_e64 v40, v40, v240, s[78:79]
	v_cmp_le_i32_e64 s[78:79], 51, v242
	v_cndmask_b32_e64 v41, v41, v240, s[74:75]
	v_cmp_le_i32_e64 s[74:75], 56, v242
	v_cndmask_b32_e64 v42, v42, v240, s[76:77]
	v_cmp_le_i32_e64 s[76:77], 57, v242
	v_cndmask_b32_e64 v43, v43, v240, s[78:79]
	v_cmp_le_i32_e64 s[78:79], 58, v242
	v_cndmask_b32_e64 v44, v44, v240, s[74:75]
	v_cmp_le_i32_e64 s[74:75], 59, v242
	v_cndmask_b32_e64 v45, v45, v240, s[76:77]
	v_cmp_le_i32_e64 s[76:77], 0, v242
	v_cndmask_b32_e64 v46, v46, v240, s[78:79]
	v_cmp_le_i32_e64 s[78:79], 1, v242
	v_cndmask_b32_e64 v47, v47, v240, s[74:75]
	v_cmp_le_i32_e64 s[74:75], 2, v242
	v_cndmask_b32_e64 v48, v48, v240, s[76:77]
	v_cmp_le_i32_e64 s[76:77], 3, v242
	v_cndmask_b32_e64 v49, v49, v240, s[78:79]
	v_cmp_le_i32_e64 s[78:79], 8, v242
	v_cndmask_b32_e64 v50, v50, v240, s[74:75]
	v_cmp_le_i32_e64 s[74:75], 9, v242
	v_cndmask_b32_e64 v51, v51, v240, s[76:77]
	v_cmp_le_i32_e64 s[76:77], 10, v242
	v_cndmask_b32_e64 v52, v52, v240, s[78:79]
	v_cmp_le_i32_e64 s[78:79], 11, v242
	v_cndmask_b32_e64 v53, v53, v240, s[74:75]
	v_cmp_le_i32_e64 s[74:75], 16, v242
	v_cndmask_b32_e64 v54, v54, v240, s[76:77]
	v_cmp_le_i32_e64 s[76:77], 17, v242
	v_cndmask_b32_e64 v55, v55, v240, s[78:79]
	v_cmp_le_i32_e64 s[78:79], 18, v242
	v_cndmask_b32_e64 v56, v56, v240, s[74:75]
	v_cmp_le_i32_e64 s[74:75], 19, v242
	v_cndmask_b32_e64 v57, v57, v240, s[76:77]
	v_cmp_le_i32_e64 s[76:77], 24, v242
	v_cndmask_b32_e64 v58, v58, v240, s[78:79]
	v_cmp_le_i32_e64 s[78:79], 25, v242
	v_cndmask_b32_e64 v59, v59, v240, s[74:75]
	v_cmp_le_i32_e64 s[74:75], 26, v242
	v_cndmask_b32_e64 v60, v60, v240, s[76:77]
	v_cmp_le_i32_e64 s[76:77], 27, v242
	s_nop 0
	v_cndmask_b32_e64 v61, v61, v240, s[78:79]
	v_cndmask_b32_e64 v62, v62, v240, s[74:75]
	v_cndmask_b32_e64 v63, v63, v240, s[76:77]

; DI f32x16 mma32(bf16x8 a, bf16x8 b, f32x16 c) { return __builtin_amdgcn_mfma_f32_32x32x16_bf16(a, b, c, 0, 0, 0); }
; DI bf16x8 packp(const f32x16& x, const int h8) { v4u p; p.x = pk2(x[h8 + 0], x[h8 + 1]); p.y = pk2(x[h8 + 2], x[h8 + 3]); p.z = pk2(x[h8 + 4], x[h8 + 5]); p.w = pk2(x[h8 + 6], x[h8 + 7]); return __builtin_bit_cast(bf16x8, p); }
; DI void nsa_item(KA a, LAS unsigned char* lds, const int it) {
;     ...
;         f32x2 ls2 = {0.f, 0.f};
; #pragma unroll
;         for (int kt = 0; kt < 2; ++kt)
; #pragma unroll
;             for (int i2 = 0; i2 < 16; i2 += 2) { const float p0 = __builtin_amdgcn_exp2f(st[kt][i2]), p1 = __builtin_amdgcn_exp2f(st[kt][i2 + 1]); st[kt][i2] = p0; st[kt][i2 + 1] = p1; ls2 += (f32x2){p0, p1}; }
;         l_run += ls2[0] + ls2[1];
; #pragma unroll
;         for (int sp = 0; sp < 4; ++sp) { const bf16x8 pf = packp(st[sp >> 1], 8 * (sp & 1));
; #pragma unroll
;             for (int dh = 0; dh < 2; ++dh) ot[dh] = mma32(vfrag(Vc, 32 * dh + r, sp, hf), pf, ot[dh]); }
.LBB0_802:
	s_waitcnt lgkmcnt(0)
	s_barrier
	s_bitcmp1_b32 s87, 0
	s_cselect_b32 s74, 0, 0x9000
	s_movk_i32 s75, 0x4800
	s_cselect_b32 s75, s75, 0xb400
	v_add3_u32 v231, s74, v90, v130
	v_add3_u32 v230, s75, v90, v131
	ds_read_b128 v[170:173], v231 offset:64
	ds_read_b128 v[178:181], v231 offset:4608
	ds_read_b128 v[182:185], v231 offset:4640
	ds_read_b128 v[186:189], v231 offset:4672
	ds_read_b128 v[206:209], v231 offset:4704
	ds_read_b128 v[174:177], v231 offset:96
	v_exp_f32_e32 v48, v48
	v_exp_f32_e32 v49, v49
	v_exp_f32_e32 v50, v50
	v_exp_f32_e32 v51, v51
	v_exp_f32_e32 v52, v52
	v_exp_f32_e32 v53, v53
	v_exp_f32_e32 v54, v54
	v_exp_f32_e32 v55, v55
	v_cvt_pk_bf16_f32 v144, v48, v49
	v_cvt_pk_bf16_f32 v145, v50, v51
	v_cvt_pk_bf16_f32 v146, v52, v53
	v_cvt_pk_bf16_f32 v147, v54, v55
	v_exp_f32_e32 v56, v56
	v_exp_f32_e32 v57, v57
	v_mfma_f32_32x32x16_bf16 v[16:31], v[210:213], v[144:147], v[16:31]
	v_exp_f32_e32 v58, v58
	v_exp_f32_e32 v59, v59
	v_exp_f32_e32 v60, v60
	v_exp_f32_e32 v61, v61
	v_exp_f32_e32 v62, v62
	v_exp_f32_e32 v63, v63
	v_mfma_f32_32x32x16_bf16 v[0:15], v[218:221], v[144:147], v[0:15]
	v_cvt_pk_bf16_f32 v144, v56, v57
	v_cvt_pk_bf16_f32 v145, v58, v59
	v_cvt_pk_bf16_f32 v146, v60, v61
	v_cvt_pk_bf16_f32 v147, v62, v63
	v_exp_f32_e32 v32, v32
	v_exp_f32_e32 v33, v33
	v_mfma_f32_32x32x16_bf16 v[0:15], v[222:225], v[144:147], v[0:15]
	v_exp_f32_e32 v34, v34
	v_exp_f32_e32 v35, v35
	v_exp_f32_e32 v36, v36
	v_exp_f32_e32 v37, v37
	v_exp_f32_e32 v38, v38
	v_exp_f32_e32 v39, v39
	v_mfma_f32_32x32x16_bf16 v[16:31], v[214:217], v[144:147], v[16:31]
	v_cvt_pk_bf16_f32 v144, v32, v33
	v_cvt_pk_bf16_f32 v145, v34, v35
	v_cvt_pk_bf16_f32 v146, v36, v37
	v_cvt_pk_bf16_f32 v147, v38, v39
	v_exp_f32_e32 v40, v40
	v_exp_f32_e32 v41, v41
	v_exp_f32_e32 v42, v42
	v_mfma_f32_32x32x16_bf16 v[16:31], v[226:229], v[144:147], v[16:31]
	v_exp_f32_e32 v43, v43
	v_exp_f32_e32 v44, v44
	v_exp_f32_e32 v45, v45
	v_exp_f32_e32 v46, v46
	v_exp_f32_e32 v47, v47
	s_add_i32 s76, s87, 1
	v_mfma_f32_32x32x16_bf16 v[0:15], v[152:155], v[144:147], v[0:15]
	v_cvt_pk_bf16_f32 v144, v40, v41
	v_cvt_pk_bf16_f32 v145, v42, v43
	v_cvt_pk_bf16_f32 v146, v44, v45
	v_cvt_pk_bf16_f32 v147, v46, v47
	s_cmp_ge_i32 s76, s84
	s_nop 0
	v_mfma_f32_32x32x16_bf16 v[16:31], v[246:249], v[144:147], v[16:31]
	v_mfma_f32_32x32x16_bf16 v[0:15], v[148:151], v[144:147], v[0:15]
